# P0 x-row loop: wave sum by DPP row reduction (row_shr 1/2/4/8 + row_bcast 15/31, total read from lane 63) instead of six ds_bpermute round trips
# baseline (speedup 1.0000x reference)
.LBB0_14:
	s_waitcnt lgkmcnt(0)
	global_load_dwordx4 v[14:17], v2, s[4:5]
	global_load_dwordx4 v[18:21], v2, s[4:5] offset:1024
	global_load_dwordx4 v[22:25], v2, s[4:5] offset:2048
	global_load_dwordx4 v[26:29], v2, s[4:5] offset:3072
	v_lshl_add_u64 v[30:31], s[4:5], 0, v[2:3]
	v_add_co_u32_e32 v42, vcc, s24, v30
	s_lshl_b64 s[4:5], s[18:19], 12
	s_nop 0
	v_addc_co_u32_e32 v43, vcc, 0, v31, vcc
	global_load_dwordx4 v[30:33], v[42:43], off
	global_load_dwordx4 v[34:37], v[42:43], off offset:1024
	global_load_dwordx4 v[38:41], v[42:43], off offset:2048
	s_nop 0
	global_load_dwordx4 v[42:45], v[42:43], off offset:3072
	s_waitcnt vmcnt(7)
	v_mul_f32_e32 v13, v15, v15
	v_mul_f32_e32 v46, v17, v17
	s_waitcnt vmcnt(6)
	v_mul_f32_e32 v47, v19, v19
	v_mul_f32_e32 v48, v21, v21
	s_waitcnt vmcnt(5)
	v_mul_f32_e32 v49, v23, v23
	v_mul_f32_e32 v50, v25, v25
	v_fmac_f32_e32 v13, v14, v14
	v_fmac_f32_e32 v46, v16, v16
	v_fmac_f32_e32 v47, v18, v18
	v_fmac_f32_e32 v48, v20, v20
	s_waitcnt vmcnt(4)
	v_mul_f32_e32 v51, v27, v27
	v_mul_f32_e32 v52, v29, v29
	v_fmac_f32_e32 v49, v22, v22
	v_fmac_f32_e32 v50, v24, v24
	v_add_f32_e32 v13, v13, v46
	v_add_f32_e32 v46, v47, v48
	v_fmac_f32_e32 v51, v26, v26
	v_fmac_f32_e32 v52, v28, v28
	v_add_f32_e32 v47, v49, v50
	s_waitcnt vmcnt(3)
	v_mul_f32_e32 v49, v31, v31
	v_mul_f32_e32 v50, v33, v33
	v_add_f32_e32 v13, v13, v46
	v_add_f32_e32 v48, v51, v52
	s_waitcnt vmcnt(2)
	v_mul_f32_e32 v51, v35, v35
	v_mul_f32_e32 v52, v37, v37
	v_fmac_f32_e32 v49, v30, v30
	v_fmac_f32_e32 v50, v32, v32
	v_add_f32_e32 v13, v13, v47
	s_waitcnt vmcnt(1)
	v_mul_f32_e32 v53, v39, v39
	v_mul_f32_e32 v54, v41, v41
	v_fmac_f32_e32 v51, v34, v34
	v_fmac_f32_e32 v52, v36, v36
	v_add_f32_e32 v46, v49, v50
	v_add_f32_e32 v13, v13, v48
	s_waitcnt vmcnt(0)
	v_mul_f32_e32 v55, v43, v43
	v_mul_f32_e32 v56, v45, v45
	v_fmac_f32_e32 v53, v38, v38
	v_fmac_f32_e32 v54, v40, v40
	v_add_f32_e32 v47, v51, v52
	v_add_f32_e32 v13, v13, v46
	v_fmac_f32_e32 v55, v42, v42
	v_fmac_f32_e32 v56, v44, v44
	v_add_f32_e32 v49, v53, v54
	v_add_f32_e32 v13, v13, v47
	v_add_f32_e32 v50, v55, v56
	v_add_f32_e32 v13, v13, v49
	v_add_f32_e32 v13, v13, v50
	s_nop 1
	v_add_f32_dpp v13, v13, v13 row_shr:1 row_mask:0xf bank_mask:0xf bound_ctrl:1
	v_cvt_pk_bf16_f32 v14, v14, v15
	v_cvt_pk_bf16_f32 v15, v16, v17
	v_cvt_pk_bf16_f32 v16, v18, v19
	v_cvt_pk_bf16_f32 v18, v22, v23
	s_waitcnt lgkmcnt(0)
	s_nop 0
	s_nop 1
	v_add_f32_dpp v13, v13, v13 row_shr:2 row_mask:0xf bank_mask:0xf bound_ctrl:1
	v_lshl_add_u64 v[46:47], v[4:5], 0, s[4:5]
	v_cvt_pk_bf16_f32 v17, v20, v21
	v_cvt_pk_bf16_f32 v19, v24, v25
	global_store_dwordx2 v[46:47], v[14:15], off
	global_store_dwordx2 v[46:47], v[16:17], off offset:512
	global_store_dwordx2 v[46:47], v[18:19], off offset:1024
	s_waitcnt lgkmcnt(0)
	s_nop 0
	s_nop 1
	v_add_f32_dpp v13, v13, v13 row_shr:4 row_mask:0xf bank_mask:0xf bound_ctrl:1
	v_cvt_pk_bf16_f32 v20, v26, v27
	v_cvt_pk_bf16_f32 v21, v28, v29
	v_cvt_pk_bf16_f32 v14, v30, v31
	v_cvt_pk_bf16_f32 v15, v32, v33
	s_waitcnt lgkmcnt(0)
	s_nop 0
	s_nop 1
	v_add_f32_dpp v13, v13, v13 row_shr:8 row_mask:0xf bank_mask:0xf bound_ctrl:1
	global_store_dwordx2 v[46:47], v[20:21], off offset:1536
	v_cvt_pk_bf16_f32 v16, v34, v35
	v_cvt_pk_bf16_f32 v18, v38, v39
	s_waitcnt lgkmcnt(0)
	s_nop 0
	s_nop 1
	v_add_f32_dpp v13, v13, v13 row_bcast:15 row_mask:0xa bank_mask:0xf
	v_cvt_pk_bf16_f32 v17, v36, v37
	global_store_dwordx2 v[46:47], v[14:15], off offset:2048
	global_store_dwordx2 v[46:47], v[16:17], off offset:2560
	v_cvt_pk_bf16_f32 v16, v42, v43
	v_cvt_pk_bf16_f32 v17, v44, v45
	s_waitcnt lgkmcnt(0)
	s_nop 0
	s_nop 1
	v_add_f32_dpp v13, v13, v13 row_bcast:31 row_mask:0xc bank_mask:0xf
	v_cvt_pk_bf16_f32 v19, v40, v41
	global_store_dwordx2 v[46:47], v[18:19], off offset:3072
	global_store_dwordx2 v[46:47], v[16:17], off offset:3584
	s_and_saveexec_b64 s[20:21], s[2:3]
	s_cbranch_execz .LBB0_11
	s_waitcnt lgkmcnt(0)
	v_readlane_b32 s4, v13, 63
	s_nop 1
	v_mov_b32_e32 v13, s4
	v_fmamk_f32 v13, v13, 0x3a000000, v11
	v_mul_f32_e32 v14, 0x4f800000, v13
	v_cmp_gt_f32_e32 vcc, s25, v13
	s_nop 1
	v_cndmask_b32_e32 v13, v13, v14, vcc
	v_sqrt_f32_e32 v14, v13
	s_nop 0
	v_add_u32_e32 v15, -1, v14
	v_fma_f32 v17, -v15, v14, v13
	v_add_u32_e32 v16, 1, v14
	v_cmp_ge_f32_e64 s[4:5], 0, v17
	s_nop 1
	v_cndmask_b32_e64 v15, v14, v15, s[4:5]
	v_fma_f32 v14, -v16, v14, v13
	v_cmp_lt_f32_e64 s[4:5], 0, v14
	s_nop 1
	v_cndmask_b32_e64 v14, v15, v16, s[4:5]
	v_mul_f32_e32 v15, 0x37800000, v14
	v_cndmask_b32_e32 v14, v14, v15, vcc
	v_cmp_class_f32_e32 vcc, v13, v12
	s_nop 1
	v_cndmask_b32_e32 v13, v14, v13, vcc
	v_div_scale_f32 v14, s[4:5], v13, v13, 1.0
	v_rcp_f32_e32 v15, v14
	s_lshl_b64 s[4:5], s[18:19], 2
	s_add_u32 s4, s22, s4
	s_addc_u32 s5, s23, s5
	v_fma_f32 v16, -v14, v15, 1.0
	v_fmac_f32_e32 v15, v16, v15
	v_div_scale_f32 v16, vcc, 1.0, v13, 1.0
	v_mul_f32_e32 v17, v16, v15
	v_fma_f32 v18, -v14, v17, v16
	v_fmac_f32_e32 v17, v18, v15
	v_fma_f32 v14, -v14, v17, v16
	v_div_fmas_f32 v14, v14, v15, v17
	v_div_fixup_f32 v13, v14, v13, 1.0
	global_store_dword v3, v13, s[4:5]
	s_branch .LBB0_11
